# even-step first K pair: read order swapped and counted lgkmcnt(1)/(0) so the first QK MFMA starts after one LDS return
# speedup vs baseline: 1.0056x; 1.0048x over previous
; __device__ __forceinline__ void partialSM(f32x16& p0, f32x16& p1, float& mhat, f32x16& negm, float& alpha, const bool first) {
;     ...
;     for (int r = 0; r < 16; ++r) p0[r] = __builtin_amdgcn_exp2f(p0[r]);
; }
; __device__ __forceinline__ void finishSM(f32x16& p0, f32x16& p1, float alpha, float& l_reg, bf16x8& pa0, bf16x8& pa1, bf16x8& pa2, bf16x8& pa3) {
; #pragma unroll
;     for (int r = 0; r < 16; ++r) p1[r] = __builtin_amdgcn_exp2f(p1[r]);
;     float ps = 0;
; #pragma unroll
;     for (int r = 0; r < 16; ++r) ps += p0[r];
; #pragma unroll
;     for (int r = 0; r < 16; ++r) ps += p1[r];
;     { auto rr = __builtin_amdgcn_permlane32_swap(__float_as_uint(ps), __float_as_uint(ps), false, false);
;       ps = __uint_as_float(rr[0]) + __uint_as_float(rr[1]); }
;     l_reg = l_reg * alpha + ps;
.LBB0_598:
	v_exp_f32_e32 v2, v128
	v_exp_f32_e32 v3, v129
	v_exp_f32_e32 v4, v130
	v_exp_f32_e32 v5, v131
	v_exp_f32_e32 v6, v132
	v_add_f32_e32 v132, 0, v2
	v_exp_f32_e32 v7, v133
	v_add_f32_e32 v132, v3, v132
	v_exp_f32_e32 v8, v134
	v_add_f32_e32 v132, v4, v132
	v_exp_f32_e32 v9, v135
	v_add_f32_e32 v132, v5, v132
	v_exp_f32_e32 v10, v136
	v_add_f32_e32 v132, v6, v132
	v_exp_f32_e32 v11, v137
	v_add_f32_e32 v132, v7, v132
	v_exp_f32_e32 v12, v138
	v_add_f32_e32 v132, v8, v132
	v_exp_f32_e32 v13, v139
	v_add_f32_e32 v132, v9, v132
	v_exp_f32_e32 v128, v140
	v_add_f32_e32 v132, v10, v132
	v_exp_f32_e32 v129, v141
	v_add_f32_e32 v132, v11, v132
	v_exp_f32_e32 v130, v142
	v_add_f32_e32 v132, v12, v132
	v_exp_f32_e32 v131, v143
	v_add_f32_e32 v132, v13, v132
	v_exp_f32_e32 v112, v112
	v_add_f32_e32 v132, v128, v132
	v_exp_f32_e32 v113, v113
	v_add_f32_e32 v132, v129, v132
	v_exp_f32_e32 v114, v114
	v_add_f32_e32 v132, v130, v132
	v_exp_f32_e32 v115, v115
	v_add_f32_e32 v132, v131, v132
	v_exp_f32_e32 v116, v116
	v_add_f32_e32 v132, v112, v132
	v_exp_f32_e32 v117, v117
	v_add_f32_e32 v132, v113, v132
	v_exp_f32_e32 v118, v118
	v_add_f32_e32 v132, v114, v132
	v_exp_f32_e32 v119, v119
	v_add_f32_e32 v132, v115, v132
	v_exp_f32_e32 v120, v120
	v_add_f32_e32 v132, v116, v132
	v_exp_f32_e32 v121, v121
	v_add_f32_e32 v132, v117, v132
	v_exp_f32_e32 v122, v122
	v_add_f32_e32 v132, v118, v132
	v_exp_f32_e32 v123, v123
	v_add_f32_e32 v132, v119, v132
	v_exp_f32_e32 v124, v124
	v_add_f32_e32 v132, v120, v132
	v_exp_f32_e32 v125, v125
	v_add_f32_e32 v132, v121, v132
	v_exp_f32_e32 v126, v126
	v_add_f32_e32 v132, v122, v132
	v_exp_f32_e32 v127, v127
	v_add_f32_e32 v132, v123, v132
	v_add_f32_e32 v132, v124, v132
	v_add_f32_e32 v132, v125, v132
	v_add_f32_e32 v132, v126, v132
	v_add_f32_e32 v190, v127, v132
	s_waitcnt lgkmcnt(0)
	s_barrier
; #define LAS __attribute__((address_space(3)))
; __device__ __forceinline__ void finishSM(f32x16& p0, f32x16& p1, float alpha, float& l_reg, bf16x8& pa0, bf16x8& pa1, bf16x8& pa2, bf16x8& pa3) {
; #pragma unroll
;     for (int r = 0; r < 16; ++r) p1[r] = __builtin_amdgcn_exp2f(p1[r]);
;     float ps = 0;
; #pragma unroll
;     for (int r = 0; r < 16; ++r) ps += p0[r];
; #pragma unroll
;     for (int r = 0; r < 16; ++r) ps += p1[r];
;     { auto rr = __builtin_amdgcn_permlane32_swap(__float_as_uint(ps), __float_as_uint(ps), false, false);
;       ps = __uint_as_float(rr[0]) + __uint_as_float(rr[1]); }
;     l_reg = l_reg * alpha + ps;
;     ...
;     PK4(p0, 0, pa0); PK4(p0, 8, pa1); PK4(p1, 0, pa2); PK4(p1, 8, pa3);
;     ...
; }
; __device__ __forceinline__ void qkt(f32x16& p0, f32x16& p1, const LAS char* Ks, const bf16x8* qr, const f32x16& negm, int r32, int hi) {
; #pragma unroll
;     for (int d0 = 0; d0 < 4; ++d0) { const int cb = (d0 * 16 + hi * 8) * 2;
;         const bf16x8 b0 = *(const LAS bf16x8*)(Ks + KSWZ(r32, cb));
;         const bf16x8 b1 = *(const LAS bf16x8*)(Ks + KSWZ(32 + r32, cb));
;         if (d0 == 0) { p0 = __builtin_amdgcn_mfma_f32_32x32x16_bf16(b0, qr[0], negm, 0, 0, 0); p1 = __builtin_amdgcn_mfma_f32_32x32x16_bf16(b1, qr[0], negm, 0, 0, 0); }
;         else { p0 = __builtin_amdgcn_mfma_f32_32x32x16_bf16(b0, qr[d0], p0, 0, 0, 0); p1 = __builtin_amdgcn_mfma_f32_32x32x16_bf16(b1, qr[d0], p1, 0, 0, 0); } }
; }
; __device__ __forceinline__ int v_st(int k, int c) { const int kk = (k & ~0xC) | ((k & 4) << 1) | ((k & 8) >> 1); return ((kk >> 3) * 4 + (c >> 5)) * 512 + ((kk & 7) * 32 + (c & 31)) * 2; }
; __device__ __forceinline__ int v_rd_base(int lane) { return ((lane & 3) << 3) | (((lane >> 2) & 3) << 6) | (((lane >> 4) & 1) << 5) | (((lane >> 5) & 1) << 8); }
; template <int OFF> __device__ __forceinline__ s16x4 tr_read(int vb) {
;     s16x4 r; asm volatile("ds_read_b64_tr_b16 %0, %1 offset:%2" : "=&v"(r) : "v"(vb), "i"(OFF) : "memory"); return r;
; }
; template <int D0> __device__ __forceinline__ void pv_one(f32x16& od, int vb, bf16x8 pa0, bf16x8 pa1, bf16x8 pa2, bf16x8 pa3) {
;     const s16x4 l0 = tr_read<v_rd_off(D0, 0, 0)>(vb), h0 = tr_read<v_rd_off(D0, 0, 1)>(vb), l1 = tr_read<v_rd_off(D0, 1, 0)>(vb), h1 = tr_read<v_rd_off(D0, 1, 1)>(vb);
	v_mov_b32_e32 v191, v190
	s_nop 1
	v_permlane32_swap_b32_e32 v190, v191
	v_cvt_pk_bf16_f32 v2, v2, v3
	v_cvt_pk_bf16_f32 v3, v4, v5
	v_cvt_pk_bf16_f32 v4, v6, v7
	v_cvt_pk_bf16_f32 v5, v8, v9
	v_cvt_pk_bf16_f32 v6, v10, v11
	v_cvt_pk_bf16_f32 v7, v12, v13
	v_cvt_pk_bf16_f32 v8, v128, v129
	v_cvt_pk_bf16_f32 v9, v130, v131
	v_cvt_pk_bf16_f32 v10, v112, v113
	v_cvt_pk_bf16_f32 v11, v114, v115
	v_cvt_pk_bf16_f32 v12, v116, v117
	v_cvt_pk_bf16_f32 v13, v118, v119
	v_cvt_pk_bf16_f32 v184, v120, v121
	v_cvt_pk_bf16_f32 v185, v122, v123
	v_cvt_pk_bf16_f32 v186, v124, v125
	v_cvt_pk_bf16_f32 v187, v126, v127
	v_permlane32_swap_b32_e32 v2, v4
	v_permlane32_swap_b32_e32 v3, v5
	v_permlane32_swap_b32_e32 v6, v8
	v_permlane32_swap_b32_e32 v7, v9
	v_permlane32_swap_b32_e32 v10, v12
	v_permlane32_swap_b32_e32 v11, v13
	v_permlane32_swap_b32_e32 v184, v186
	v_permlane32_swap_b32_e32 v185, v187
	s_setprio 1
	s_and_b32 s4, s38, 0x6000
	v_add_u32_e32 v200, s4, v241
	v_add_u32_e32 v220, v200, v237
	ds_read_b128 v[112:115], v220
	ds_read_b128 v[192:195], v220 offset:4096
	v_add_u32_e32 v196, v200, v238
	s_waitcnt lgkmcnt(1)
	v_mfma_f32_32x32x16_bf16 v[128:143], v[112:115], v[156:159], v[96:111]
	s_waitcnt lgkmcnt(0)
	v_mfma_f32_32x32x16_bf16 v[112:127], v[192:195], v[156:159], v[96:111]
	ds_read_b128 v[192:195], v196 offset:4096
	ds_read_b128 v[196:199], v196
	s_waitcnt lgkmcnt(1)
	v_mfma_f32_32x32x16_bf16 v[112:127], v[192:195], v[152:155], v[112:127]
	s_waitcnt lgkmcnt(0)
	v_mfma_f32_32x32x16_bf16 v[128:143], v[196:199], v[152:155], v[128:143]
	v_add_u32_e32 v196, v200, v239
	ds_read_b128 v[192:195], v196 offset:4096
	ds_read_b128 v[196:199], v196
	s_waitcnt lgkmcnt(1)
	v_mfma_f32_32x32x16_bf16 v[112:127], v[192:195], v[148:151], v[112:127]
	s_waitcnt lgkmcnt(0)
	v_mfma_f32_32x32x16_bf16 v[128:143], v[196:199], v[148:151], v[128:143]
	v_add_u32_e32 v196, v200, v240
	ds_read_b128 v[192:195], v196 offset:4096
	ds_read_b128 v[196:199], v196
	v_lshl_add_u32 v200, s61, 14, v242
	ds_read_b64_tr_b16 v[172:173], v200 offset:0
	ds_read_b64_tr_b16 v[174:175], v200 offset:0x800
	ds_read_b64_tr_b16 v[176:177], v200 offset:0x1000
	ds_read_b64_tr_b16 v[178:179], v200 offset:0x1800
	s_waitcnt lgkmcnt(5)
	v_mfma_f32_32x32x16_bf16 v[112:127], v[192:195], v[144:147], v[112:127]
	ds_read_b64_tr_b16 v[220:221], v200 offset:0x2000
	ds_read_b64_tr_b16 v[222:223], v200 offset:0x2800
	s_waitcnt lgkmcnt(6)
	v_mfma_f32_32x32x16_bf16 v[128:143], v[196:199], v[144:147], v[128:143]
	ds_read_b64_tr_b16 v[244:245], v200 offset:0x3000
	ds_read_b64_tr_b16 v[246:247], v200 offset:0x3800
	s_waitcnt lgkmcnt(6)
	v_mfma_f32_32x32x16_bf16 v[64:79], v[2:5], v[172:175], v[64:79]
	ds_read_b64_tr_b16 v[192:193], v200 offset:0x200
	ds_read_b64_tr_b16 v[194:195], v200 offset:0xa00
	s_waitcnt lgkmcnt(6)
	v_mfma_f32_32x32x16_bf16 v[64:79], v[6:9], v[176:179], v[64:79]
	ds_read_b64_tr_b16 v[196:197], v200 offset:0x1200
	ds_read_b64_tr_b16 v[198:199], v200 offset:0x1a00
	s_waitcnt lgkmcnt(6)
	v_mfma_f32_32x32x16_bf16 v[64:79], v[10:13], v[220:223], v[64:79]
	ds_read_b64_tr_b16 v[220:221], v200 offset:0x2200
	ds_read_b64_tr_b16 v[222:223], v200 offset:0x2a00
	s_waitcnt lgkmcnt(6)
	v_mfma_f32_32x32x16_bf16 v[64:79], v[184:187], v[244:247], v[64:79]
	ds_read_b64_tr_b16 v[244:245], v200 offset:0x3200
	ds_read_b64_tr_b16 v[246:247], v200 offset:0x3a00
	s_waitcnt lgkmcnt(6)
	v_mfma_f32_32x32x16_bf16 v[48:63], v[2:5], v[192:195], v[48:63]
	ds_read_b64_tr_b16 v[192:193], v200 offset:0x400
	ds_read_b64_tr_b16 v[194:195], v200 offset:0xc00
	s_waitcnt lgkmcnt(6)
	v_mfma_f32_32x32x16_bf16 v[48:63], v[6:9], v[196:199], v[48:63]
	ds_read_b64_tr_b16 v[196:197], v200 offset:0x1400
	ds_read_b64_tr_b16 v[198:199], v200 offset:0x1c00
	s_waitcnt lgkmcnt(6)
	v_mfma_f32_32x32x16_bf16 v[48:63], v[10:13], v[220:223], v[48:63]
	ds_read_b64_tr_b16 v[220:221], v200 offset:0x2400
	ds_read_b64_tr_b16 v[222:223], v200 offset:0x2c00
	s_waitcnt lgkmcnt(6)
	v_mfma_f32_32x32x16_bf16 v[48:63], v[184:187], v[244:247], v[48:63]
	ds_read_b64_tr_b16 v[244:245], v200 offset:0x3400
	ds_read_b64_tr_b16 v[246:247], v200 offset:0x3c00
	s_waitcnt lgkmcnt(6)
	v_mfma_f32_32x32x16_bf16 v[32:47], v[2:5], v[192:195], v[32:47]
	ds_read_b64_tr_b16 v[192:193], v200 offset:0x600
	ds_read_b64_tr_b16 v[194:195], v200 offset:0xe00
	s_waitcnt lgkmcnt(6)
	v_mfma_f32_32x32x16_bf16 v[32:47], v[6:9], v[196:199], v[32:47]
	ds_read_b64_tr_b16 v[196:197], v200 offset:0x1600
	ds_read_b64_tr_b16 v[198:199], v200 offset:0x1e00
	s_waitcnt lgkmcnt(6)
	v_mfma_f32_32x32x16_bf16 v[32:47], v[10:13], v[220:223], v[32:47]
	ds_read_b64_tr_b16 v[220:221], v200 offset:0x2600
	ds_read_b64_tr_b16 v[222:223], v200 offset:0x2e00
	s_waitcnt lgkmcnt(6)
	v_mfma_f32_32x32x16_bf16 v[32:47], v[184:187], v[244:247], v[32:47]
	ds_read_b64_tr_b16 v[244:245], v200 offset:0x3600
	ds_read_b64_tr_b16 v[246:247], v200 offset:0x3e00
	s_waitcnt lgkmcnt(6)
	v_mfma_f32_32x32x16_bf16 v[16:31], v[2:5], v[192:195], v[16:31]
	s_waitcnt lgkmcnt(4)
	v_mfma_f32_32x32x16_bf16 v[16:31], v[6:9], v[196:199], v[16:31]
	s_waitcnt lgkmcnt(2)
	v_mfma_f32_32x32x16_bf16 v[16:31], v[10:13], v[220:223], v[16:31]
	s_waitcnt lgkmcnt(0)
	v_mfma_f32_32x32x16_bf16 v[16:31], v[184:187], v[244:247], v[16:31]
	s_setprio 0
	s_waitcnt lgkmcnt(0)
	s_barrier
	s_andn2_b64 vcc, exec, s[2:3]
	s_cbranch_vccnz .LBB0_600
	s_and_b32 s2, s49, 3
	s_lshl_b32 s3, s2, 14
	s_add_i32 s3, s3, 0
	v_add_u32_e32 v2, s3, v233
	v_add_u32_e32 v3, s3, v234
	v_lshl_add_u32 v4, s2, 13, v235
	s_waitcnt vmcnt(2)
	ds_write_b128 v2, v[160:163]
	s_waitcnt vmcnt(1)
	ds_write_b128 v3, v[164:167]
	s_waitcnt vmcnt(0)
	ds_write_b128 v4, v[168:171]

; __device__ __forceinline__ void partialSM(f32x16& p0, f32x16& p1, float& mhat, f32x16& negm, float& alpha, const bool first) {
;     ...
;     for (int r = 0; r < 16; ++r) p0[r] = __builtin_amdgcn_exp2f(p0[r]);
; }
; __device__ __forceinline__ void finishSM(f32x16& p0, f32x16& p1, float alpha, float& l_reg, bf16x8& pa0, bf16x8& pa1, bf16x8& pa2, bf16x8& pa3) {
; #pragma unroll
;     for (int r = 0; r < 16; ++r) p1[r] = __builtin_amdgcn_exp2f(p1[r]);
;     float ps = 0;
; #pragma unroll
;     for (int r = 0; r < 16; ++r) ps += p0[r];
; #pragma unroll
;     for (int r = 0; r < 16; ++r) ps += p1[r];
;     { auto rr = __builtin_amdgcn_permlane32_swap(__float_as_uint(ps), __float_as_uint(ps), false, false);
;       ps = __uint_as_float(rr[0]) + __uint_as_float(rr[1]); }
;     l_reg = l_reg * alpha + ps;
.LBB0_629:
	v_exp_f32_e32 v2, v128
	v_exp_f32_e32 v3, v129
	v_exp_f32_e32 v4, v130
	v_exp_f32_e32 v5, v131
	v_exp_f32_e32 v6, v132
	v_add_f32_e32 v132, 0, v2
	v_exp_f32_e32 v7, v133
	v_add_f32_e32 v132, v3, v132
	v_exp_f32_e32 v8, v134
	v_add_f32_e32 v132, v4, v132
	v_exp_f32_e32 v9, v135
	v_add_f32_e32 v132, v5, v132
	v_exp_f32_e32 v10, v136
	v_add_f32_e32 v132, v6, v132
	v_exp_f32_e32 v11, v137
	v_add_f32_e32 v132, v7, v132
	v_exp_f32_e32 v12, v138
	v_add_f32_e32 v132, v8, v132
	v_exp_f32_e32 v13, v139
	v_add_f32_e32 v132, v9, v132
	v_exp_f32_e32 v128, v140
	v_add_f32_e32 v132, v10, v132
	v_exp_f32_e32 v129, v141
	v_add_f32_e32 v132, v11, v132
	v_exp_f32_e32 v130, v142
	v_add_f32_e32 v132, v12, v132
	v_exp_f32_e32 v131, v143
	v_add_f32_e32 v132, v13, v132
	v_exp_f32_e32 v112, v112
	v_add_f32_e32 v132, v128, v132
	v_exp_f32_e32 v113, v113
	v_add_f32_e32 v132, v129, v132
	v_exp_f32_e32 v114, v114
	v_add_f32_e32 v132, v130, v132
	v_exp_f32_e32 v115, v115
	v_add_f32_e32 v132, v131, v132
	v_exp_f32_e32 v116, v116
	v_add_f32_e32 v132, v112, v132
	v_exp_f32_e32 v117, v117
	v_add_f32_e32 v132, v113, v132
	v_exp_f32_e32 v118, v118
	v_add_f32_e32 v132, v114, v132
	v_exp_f32_e32 v119, v119
	v_add_f32_e32 v132, v115, v132
	v_exp_f32_e32 v120, v120
	v_add_f32_e32 v132, v116, v132
	v_exp_f32_e32 v121, v121
	v_add_f32_e32 v132, v117, v132
	v_exp_f32_e32 v122, v122
	v_add_f32_e32 v132, v118, v132
	v_exp_f32_e32 v123, v123
	v_add_f32_e32 v132, v119, v132
	v_exp_f32_e32 v124, v124
	v_add_f32_e32 v132, v120, v132
	v_exp_f32_e32 v125, v125
	v_add_f32_e32 v132, v121, v132
	v_exp_f32_e32 v126, v126
	v_add_f32_e32 v132, v122, v132
	v_exp_f32_e32 v127, v127
	v_add_f32_e32 v132, v123, v132
	v_add_f32_e32 v132, v124, v132
	v_add_f32_e32 v132, v125, v132
	v_add_f32_e32 v132, v126, v132
	v_add_f32_e32 v190, v127, v132
	s_waitcnt lgkmcnt(0)
	s_barrier
; #define LAS __attribute__((address_space(3)))
; __device__ __forceinline__ void finishSM(f32x16& p0, f32x16& p1, float alpha, float& l_reg, bf16x8& pa0, bf16x8& pa1, bf16x8& pa2, bf16x8& pa3) {
; #pragma unroll
;     for (int r = 0; r < 16; ++r) p1[r] = __builtin_amdgcn_exp2f(p1[r]);
;     float ps = 0;
; #pragma unroll
;     for (int r = 0; r < 16; ++r) ps += p0[r];
; #pragma unroll
;     for (int r = 0; r < 16; ++r) ps += p1[r];
;     { auto rr = __builtin_amdgcn_permlane32_swap(__float_as_uint(ps), __float_as_uint(ps), false, false);
;       ps = __uint_as_float(rr[0]) + __uint_as_float(rr[1]); }
;     l_reg = l_reg * alpha + ps;
;     ...
;     PK4(p0, 0, pa0); PK4(p0, 8, pa1); PK4(p1, 0, pa2); PK4(p1, 8, pa3);
;     ...
; }
; __device__ __forceinline__ void qkt(f32x16& p0, f32x16& p1, const LAS char* Ks, const bf16x8* qr, const f32x16& negm, int r32, int hi) {
; #pragma unroll
;     for (int d0 = 0; d0 < 4; ++d0) { const int cb = (d0 * 16 + hi * 8) * 2;
;         const bf16x8 b0 = *(const LAS bf16x8*)(Ks + KSWZ(r32, cb));
;         const bf16x8 b1 = *(const LAS bf16x8*)(Ks + KSWZ(32 + r32, cb));
;         if (d0 == 0) { p0 = __builtin_amdgcn_mfma_f32_32x32x16_bf16(b0, qr[0], negm, 0, 0, 0); p1 = __builtin_amdgcn_mfma_f32_32x32x16_bf16(b1, qr[0], negm, 0, 0, 0); }
;         else { p0 = __builtin_amdgcn_mfma_f32_32x32x16_bf16(b0, qr[d0], p0, 0, 0, 0); p1 = __builtin_amdgcn_mfma_f32_32x32x16_bf16(b1, qr[d0], p1, 0, 0, 0); } }
; }
; __device__ __forceinline__ int v_st(int k, int c) { const int kk = (k & ~0xC) | ((k & 4) << 1) | ((k & 8) >> 1); return ((kk >> 3) * 4 + (c >> 5)) * 512 + ((kk & 7) * 32 + (c & 31)) * 2; }
; __device__ __forceinline__ int v_rd_base(int lane) { return ((lane & 3) << 3) | (((lane >> 2) & 3) << 6) | (((lane >> 4) & 1) << 5) | (((lane >> 5) & 1) << 8); }
; template <int OFF> __device__ __forceinline__ s16x4 tr_read(int vb) {
;     s16x4 r; asm volatile("ds_read_b64_tr_b16 %0, %1 offset:%2" : "=&v"(r) : "v"(vb), "i"(OFF) : "memory"); return r;
; }
; template <int D0> __device__ __forceinline__ void pv_one(f32x16& od, int vb, bf16x8 pa0, bf16x8 pa1, bf16x8 pa2, bf16x8 pa3) {
;     const s16x4 l0 = tr_read<v_rd_off(D0, 0, 0)>(vb), h0 = tr_read<v_rd_off(D0, 0, 1)>(vb), l1 = tr_read<v_rd_off(D0, 1, 0)>(vb), h1 = tr_read<v_rd_off(D0, 1, 1)>(vb);
	v_mov_b32_e32 v191, v190
	s_nop 1
	v_permlane32_swap_b32_e32 v190, v191
	v_cvt_pk_bf16_f32 v2, v2, v3
	v_cvt_pk_bf16_f32 v3, v4, v5
	v_cvt_pk_bf16_f32 v4, v6, v7
	v_cvt_pk_bf16_f32 v5, v8, v9
	v_cvt_pk_bf16_f32 v6, v10, v11
	v_cvt_pk_bf16_f32 v7, v12, v13
	v_cvt_pk_bf16_f32 v8, v128, v129
	v_cvt_pk_bf16_f32 v9, v130, v131
	v_cvt_pk_bf16_f32 v10, v112, v113
	v_cvt_pk_bf16_f32 v11, v114, v115
	v_cvt_pk_bf16_f32 v12, v116, v117
	v_cvt_pk_bf16_f32 v13, v118, v119
	v_cvt_pk_bf16_f32 v184, v120, v121
	v_cvt_pk_bf16_f32 v185, v122, v123
	v_cvt_pk_bf16_f32 v186, v124, v125
	v_cvt_pk_bf16_f32 v187, v126, v127
	v_permlane32_swap_b32_e32 v2, v4
	v_permlane32_swap_b32_e32 v3, v5
	v_permlane32_swap_b32_e32 v6, v8
	v_permlane32_swap_b32_e32 v7, v9
	v_permlane32_swap_b32_e32 v10, v12
	v_permlane32_swap_b32_e32 v11, v13
	v_permlane32_swap_b32_e32 v184, v186
	v_permlane32_swap_b32_e32 v185, v187
	s_setprio 1
	s_and_b32 s4, s18, 0x6000
	v_add_u32_e32 v200, s4, v241
	v_add_u32_e32 v220, v200, v240
	ds_read_b128 v[112:115], v220
	ds_read_b128 v[192:195], v220 offset:4096
	v_add_u32_e32 v196, v200, v239
	s_waitcnt lgkmcnt(1)
	v_mfma_f32_32x32x16_bf16 v[128:143], v[112:115], v[156:159], v[96:111]
	s_waitcnt lgkmcnt(0)
	v_mfma_f32_32x32x16_bf16 v[112:127], v[192:195], v[156:159], v[96:111]
	ds_read_b128 v[192:195], v196 offset:4096
	ds_read_b128 v[196:199], v196
	s_waitcnt lgkmcnt(1)
	v_mfma_f32_32x32x16_bf16 v[112:127], v[192:195], v[152:155], v[112:127]
	s_waitcnt lgkmcnt(0)
	v_mfma_f32_32x32x16_bf16 v[128:143], v[196:199], v[152:155], v[128:143]
	v_add_u32_e32 v196, v200, v236
	ds_read_b128 v[192:195], v196 offset:4096
	ds_read_b128 v[196:199], v196
	s_waitcnt lgkmcnt(1)
	v_mfma_f32_32x32x16_bf16 v[112:127], v[192:195], v[148:151], v[112:127]
	s_waitcnt lgkmcnt(0)
	v_mfma_f32_32x32x16_bf16 v[128:143], v[196:199], v[148:151], v[128:143]
	v_add_u32_e32 v196, v200, v237
	ds_read_b128 v[192:195], v196 offset:4096
	ds_read_b128 v[196:199], v196
	v_lshl_add_u32 v200, s38, 14, v242
	ds_read_b64_tr_b16 v[172:173], v200 offset:0
	ds_read_b64_tr_b16 v[174:175], v200 offset:0x800
	ds_read_b64_tr_b16 v[176:177], v200 offset:0x1000
	ds_read_b64_tr_b16 v[178:179], v200 offset:0x1800
	s_waitcnt lgkmcnt(5)
	v_mfma_f32_32x32x16_bf16 v[112:127], v[192:195], v[144:147], v[112:127]
	ds_read_b64_tr_b16 v[220:221], v200 offset:0x2000
	ds_read_b64_tr_b16 v[222:223], v200 offset:0x2800
	s_waitcnt lgkmcnt(6)
	v_mfma_f32_32x32x16_bf16 v[128:143], v[196:199], v[144:147], v[128:143]
	ds_read_b64_tr_b16 v[244:245], v200 offset:0x3000
	ds_read_b64_tr_b16 v[246:247], v200 offset:0x3800
	s_waitcnt lgkmcnt(6)
	v_mfma_f32_32x32x16_bf16 v[64:79], v[2:5], v[172:175], v[64:79]
	ds_read_b64_tr_b16 v[192:193], v200 offset:0x200
	ds_read_b64_tr_b16 v[194:195], v200 offset:0xa00
	s_waitcnt lgkmcnt(6)
	v_mfma_f32_32x32x16_bf16 v[64:79], v[6:9], v[176:179], v[64:79]
	ds_read_b64_tr_b16 v[196:197], v200 offset:0x1200
	ds_read_b64_tr_b16 v[198:199], v200 offset:0x1a00
	s_waitcnt lgkmcnt(6)
	v_mfma_f32_32x32x16_bf16 v[64:79], v[10:13], v[220:223], v[64:79]
	ds_read_b64_tr_b16 v[220:221], v200 offset:0x2200
	ds_read_b64_tr_b16 v[222:223], v200 offset:0x2a00
	s_waitcnt lgkmcnt(6)
	v_mfma_f32_32x32x16_bf16 v[64:79], v[184:187], v[244:247], v[64:79]
	ds_read_b64_tr_b16 v[244:245], v200 offset:0x3200
	ds_read_b64_tr_b16 v[246:247], v200 offset:0x3a00
	s_waitcnt lgkmcnt(6)
	v_mfma_f32_32x32x16_bf16 v[48:63], v[2:5], v[192:195], v[48:63]
	ds_read_b64_tr_b16 v[192:193], v200 offset:0x400
	ds_read_b64_tr_b16 v[194:195], v200 offset:0xc00
	s_waitcnt lgkmcnt(6)
	v_mfma_f32_32x32x16_bf16 v[48:63], v[6:9], v[196:199], v[48:63]
	ds_read_b64_tr_b16 v[196:197], v200 offset:0x1400
	ds_read_b64_tr_b16 v[198:199], v200 offset:0x1c00
	s_waitcnt lgkmcnt(6)
	v_mfma_f32_32x32x16_bf16 v[48:63], v[10:13], v[220:223], v[48:63]
	ds_read_b64_tr_b16 v[220:221], v200 offset:0x2400
	ds_read_b64_tr_b16 v[222:223], v200 offset:0x2c00
	s_waitcnt lgkmcnt(6)
	v_mfma_f32_32x32x16_bf16 v[48:63], v[184:187], v[244:247], v[48:63]
	ds_read_b64_tr_b16 v[244:245], v200 offset:0x3400
	ds_read_b64_tr_b16 v[246:247], v200 offset:0x3c00
	s_waitcnt lgkmcnt(6)
	v_mfma_f32_32x32x16_bf16 v[32:47], v[2:5], v[192:195], v[32:47]
	ds_read_b64_tr_b16 v[192:193], v200 offset:0x600
	ds_read_b64_tr_b16 v[194:195], v200 offset:0xe00
	s_waitcnt lgkmcnt(6)
	v_mfma_f32_32x32x16_bf16 v[32:47], v[6:9], v[196:199], v[32:47]
	ds_read_b64_tr_b16 v[196:197], v200 offset:0x1600
	ds_read_b64_tr_b16 v[198:199], v200 offset:0x1e00
	s_waitcnt lgkmcnt(6)
	v_mfma_f32_32x32x16_bf16 v[32:47], v[10:13], v[220:223], v[32:47]
	ds_read_b64_tr_b16 v[220:221], v200 offset:0x2600
	ds_read_b64_tr_b16 v[222:223], v200 offset:0x2e00
	s_waitcnt lgkmcnt(6)
	v_mfma_f32_32x32x16_bf16 v[32:47], v[184:187], v[244:247], v[32:47]
	ds_read_b64_tr_b16 v[244:245], v200 offset:0x3600
	ds_read_b64_tr_b16 v[246:247], v200 offset:0x3e00
	s_waitcnt lgkmcnt(6)
	v_mfma_f32_32x32x16_bf16 v[16:31], v[2:5], v[192:195], v[16:31]
	s_waitcnt lgkmcnt(4)
	v_mfma_f32_32x32x16_bf16 v[16:31], v[6:9], v[196:199], v[16:31]
	s_waitcnt lgkmcnt(2)
	v_mfma_f32_32x32x16_bf16 v[16:31], v[10:13], v[220:223], v[16:31]
	s_waitcnt lgkmcnt(0)
	v_mfma_f32_32x32x16_bf16 v[16:31], v[184:187], v[244:247], v[16:31]
	s_setprio 0
	s_waitcnt lgkmcnt(0)
	s_barrier
	s_andn2_b64 vcc, exec, s[2:3]
	s_cbranch_vccnz .LBB0_631
	s_and_b32 s2, s35, 3
	s_lshl_b32 s3, s2, 14
	s_add_i32 s3, s3, 0
	v_add_u32_e32 v2, s3, v233
	v_add_u32_e32 v3, s3, v234
	v_lshl_add_u32 v4, s2, 13, v235
	s_waitcnt vmcnt(2)
	ds_write_b128 v2, v[160:163]
	s_waitcnt vmcnt(1)
	ds_write_b128 v3, v[164:167]
	s_waitcnt vmcnt(0)
	ds_write_b128 v4, v[168:171]
